# SwiGLU epilogue math re-emitted as batched f32 sequence (42 instead of ~72 instructions per 8 outputs), same formula up to f32 reassociation
# speedup vs baseline: 1.0350x; 1.0111x over previous
.LBB0_77:
	s_add_u32 s6, s26, s50
	s_addc_u32 s19, s27, s51
	s_add_u32 s6, s6, 0x100
	s_addc_u32 s19, s19, 0
	s_add_u32 s23, s10, s50
	s_addc_u32 s52, s11, s51
	s_add_i32 s82, 0, 0x10000
	v_add_u32_e32 v146, s82, v154
	ds_read_b128 v[158:161], v146
	ds_read_b128 v[162:165], v146 offset:1024
	ds_read_b128 v[166:169], v146 offset:2048
	ds_read_b128 v[170:173], v146 offset:3072
	s_cmpk_eq_i32 s50, 0x700
	s_cselect_b32 s55, s12, s19
	s_cselect_b32 s54, s31, s6
	s_cselect_b32 s53, s35, s52
	s_cselect_b32 s52, s39, s23
	v_lshl_add_u64 v[146:147], v[150:151], 0, s[50:51]
	s_add_i32 m0, s68, 0xc000
	ds_read_b128 v[174:177], v157
	ds_read_b128 v[178:181], v157 offset:1024
	ds_read_b128 v[182:185], v157 offset:2048
	ds_read_b128 v[206:209], v157 offset:3072
	ds_read_b128 v[210:213], v157 offset:4096
	ds_read_b128 v[214:217], v157 offset:5120
	ds_read_b128 v[218:221], v157 offset:6144
	ds_read_b128 v[222:225], v157 offset:7168
	global_load_lds_dwordx4 v[146:147], off
	v_lshl_add_u64 v[146:147], v[152:153], 0, s[50:51]
	s_add_i32 m0, s68, 0xe000
	s_nop 0
	global_load_lds_dwordx4 v[146:147], off
	s_add_i32 s6, 0, 0x14000
	v_add_u32_e32 v146, s6, v154
	ds_read_b128 v[226:229], v146
	ds_read_b128 v[230:233], v146 offset:1024
	ds_read_b128 v[234:237], v146 offset:2048
	ds_read_b128 v[238:241], v146 offset:3072
	s_waitcnt vmcnt(8)
	s_waitcnt lgkmcnt(0)
	s_barrier
	s_setprio 1
	v_mfma_f32_16x16x32_bf16 v[124:127], v[158:161], v[174:177], v[124:127]
	v_mfma_f32_16x16x32_bf16 v[120:123], v[166:169], v[174:177], v[120:123]
	v_mfma_f32_16x16x32_bf16 v[116:119], v[158:161], v[182:185], v[116:119]
	v_mfma_f32_16x16x32_bf16 v[112:115], v[166:169], v[182:185], v[112:115]
	v_mfma_f32_16x16x32_bf16 v[108:111], v[158:161], v[210:213], v[108:111]
	v_mfma_f32_16x16x32_bf16 v[104:107], v[166:169], v[210:213], v[104:107]
	v_mfma_f32_16x16x32_bf16 v[100:103], v[158:161], v[218:221], v[100:103]
	v_mfma_f32_16x16x32_bf16 v[96:99], v[166:169], v[218:221], v[96:99]
	v_mfma_f32_16x16x32_bf16 v[124:127], v[162:165], v[178:181], v[124:127]
	v_mfma_f32_16x16x32_bf16 v[120:123], v[170:173], v[178:181], v[120:123]
	v_mfma_f32_16x16x32_bf16 v[116:119], v[162:165], v[206:209], v[116:119]
	v_mfma_f32_16x16x32_bf16 v[112:115], v[170:173], v[206:209], v[112:115]
	v_mfma_f32_16x16x32_bf16 v[108:111], v[162:165], v[214:217], v[108:111]
	v_mfma_f32_16x16x32_bf16 v[104:107], v[170:173], v[214:217], v[104:107]
	v_mfma_f32_16x16x32_bf16 v[100:103], v[162:165], v[222:225], v[100:103]
	v_mfma_f32_16x16x32_bf16 v[96:99], v[170:173], v[222:225], v[96:99]
	v_mfma_f32_16x16x32_bf16 v[92:95], v[226:229], v[174:177], v[92:95]
	v_mfma_f32_16x16x32_bf16 v[88:91], v[234:237], v[174:177], v[88:91]
	v_mfma_f32_16x16x32_bf16 v[84:87], v[226:229], v[182:185], v[84:87]
	v_mfma_f32_16x16x32_bf16 v[80:83], v[234:237], v[182:185], v[80:83]
	v_mfma_f32_16x16x32_bf16 v[76:79], v[226:229], v[210:213], v[76:79]
	v_mfma_f32_16x16x32_bf16 v[72:75], v[234:237], v[210:213], v[72:75]
	v_mfma_f32_16x16x32_bf16 v[68:71], v[226:229], v[218:221], v[68:71]
	v_mfma_f32_16x16x32_bf16 v[64:67], v[234:237], v[218:221], v[64:67]
	v_mfma_f32_16x16x32_bf16 v[92:95], v[230:233], v[178:181], v[92:95]
	v_mfma_f32_16x16x32_bf16 v[88:91], v[238:241], v[178:181], v[88:91]
	v_mfma_f32_16x16x32_bf16 v[84:87], v[230:233], v[206:209], v[84:87]
	v_mfma_f32_16x16x32_bf16 v[80:83], v[238:241], v[206:209], v[80:83]
	v_mfma_f32_16x16x32_bf16 v[76:79], v[230:233], v[214:217], v[76:79]
	v_mfma_f32_16x16x32_bf16 v[72:75], v[238:241], v[214:217], v[72:75]
	v_mfma_f32_16x16x32_bf16 v[68:71], v[230:233], v[222:225], v[68:71]
	v_mfma_f32_16x16x32_bf16 v[64:67], v[238:241], v[222:225], v[64:67]
	s_setprio 0
	s_barrier
	s_add_i32 s19, s82, s59
	v_lshl_add_u64 v[146:147], s[52:53], 0, v[140:141]
	s_mov_b32 m0, s19
	v_lshl_add_u64 v[148:149], s[52:53], 0, v[132:133]
	global_load_lds_dwordx4 v[146:147], off
	s_add_i32 m0, s19, 0x2000
	s_nop 0
	global_load_lds_dwordx4 v[148:149], off
	s_mov_b32 m0, s68
	v_lshl_add_u64 v[194:195], s[54:55], 0, v[128:129]
	ds_read_b128 v[174:177], v157 offset:16384
	ds_read_b128 v[178:181], v157 offset:17408
	ds_read_b128 v[182:185], v157 offset:18432
	ds_read_b128 v[206:209], v157 offset:19456
	ds_read_b128 v[210:213], v157 offset:20480
	ds_read_b128 v[214:217], v157 offset:21504
	ds_read_b128 v[218:221], v157 offset:22528
	ds_read_b128 v[222:225], v157 offset:23552
	global_load_lds_dwordx4 v[194:195], off
	v_lshl_add_u64 v[196:197], s[54:55], 0, v[130:131]
	s_mov_b32 m0, s69
	s_nop 0
	global_load_lds_dwordx4 v[196:197], off
	s_add_u32 s82, s52, 0x40000
	s_addc_u32 s83, s53, 0
	s_add_i32 s6, s6, s59
	v_lshl_add_u64 v[250:251], s[82:83], 0, v[140:141]
	s_mov_b32 m0, s6
	s_nop 0
	global_load_lds_dwordx4 v[250:251], off
	v_lshl_add_u64 v[250:251], s[82:83], 0, v[132:133]
	s_add_i32 m0, s6, 0x2000
	s_nop 0
	global_load_lds_dwordx4 v[250:251], off
	s_waitcnt vmcnt(8)
	s_waitcnt lgkmcnt(0)
	s_barrier
	s_setprio 1
	v_mfma_f32_16x16x32_bf16 v[60:63], v[158:161], v[174:177], v[60:63]
	v_mfma_f32_16x16x32_bf16 v[56:59], v[166:169], v[174:177], v[56:59]
	v_mfma_f32_16x16x32_bf16 v[52:55], v[158:161], v[182:185], v[52:55]
	v_mfma_f32_16x16x32_bf16 v[48:51], v[166:169], v[182:185], v[48:51]
	v_mfma_f32_16x16x32_bf16 v[44:47], v[158:161], v[210:213], v[44:47]
	v_mfma_f32_16x16x32_bf16 v[40:43], v[166:169], v[210:213], v[40:43]
	v_mfma_f32_16x16x32_bf16 v[36:39], v[158:161], v[218:221], v[36:39]
	v_mfma_f32_16x16x32_bf16 v[32:35], v[166:169], v[218:221], v[32:35]
	v_mfma_f32_16x16x32_bf16 v[60:63], v[162:165], v[178:181], v[60:63]
	v_mfma_f32_16x16x32_bf16 v[56:59], v[170:173], v[178:181], v[56:59]
	v_mfma_f32_16x16x32_bf16 v[52:55], v[162:165], v[206:209], v[52:55]
	v_mfma_f32_16x16x32_bf16 v[48:51], v[170:173], v[206:209], v[48:51]
	v_mfma_f32_16x16x32_bf16 v[44:47], v[162:165], v[214:217], v[44:47]
	v_mfma_f32_16x16x32_bf16 v[40:43], v[170:173], v[214:217], v[40:43]
	v_mfma_f32_16x16x32_bf16 v[36:39], v[162:165], v[222:225], v[36:39]
	v_mfma_f32_16x16x32_bf16 v[32:35], v[170:173], v[222:225], v[32:35]
	v_mfma_f32_16x16x32_bf16 v[28:31], v[226:229], v[174:177], v[28:31]
	v_mfma_f32_16x16x32_bf16 v[24:27], v[234:237], v[174:177], v[24:27]
	v_mfma_f32_16x16x32_bf16 v[20:23], v[226:229], v[182:185], v[20:23]
	v_mfma_f32_16x16x32_bf16 v[16:19], v[234:237], v[182:185], v[16:19]
	v_mfma_f32_16x16x32_bf16 v[12:15], v[226:229], v[210:213], v[12:15]
	v_mfma_f32_16x16x32_bf16 v[8:11], v[234:237], v[210:213], v[8:11]
	v_mfma_f32_16x16x32_bf16 v[4:7], v[226:229], v[218:221], v[4:7]
	v_mfma_f32_16x16x32_bf16 v[0:3], v[234:237], v[218:221], v[0:3]
	v_mfma_f32_16x16x32_bf16 v[28:31], v[230:233], v[178:181], v[28:31]
	v_mfma_f32_16x16x32_bf16 v[24:27], v[238:241], v[178:181], v[24:27]
	v_mfma_f32_16x16x32_bf16 v[20:23], v[230:233], v[206:209], v[20:23]
	v_mfma_f32_16x16x32_bf16 v[16:19], v[238:241], v[206:209], v[16:19]
	v_mfma_f32_16x16x32_bf16 v[12:15], v[230:233], v[214:217], v[12:15]
	v_mfma_f32_16x16x32_bf16 v[8:11], v[238:241], v[214:217], v[8:11]
	v_mfma_f32_16x16x32_bf16 v[4:7], v[230:233], v[222:225], v[4:7]
	v_mfma_f32_16x16x32_bf16 v[0:3], v[238:241], v[222:225], v[0:3]
	s_setprio 0
	s_barrier
	s_add_i32 s6, 0, 0x18000
	v_add_u32_e32 v170, s6, v154
	ds_read_b128 v[158:161], v170
	ds_read_b128 v[162:165], v170 offset:1024
	ds_read_b128 v[166:169], v170 offset:2048
	ds_read_b128 v[170:173], v170 offset:3072
	s_add_u32 s54, s54, 0x40000
	s_addc_u32 s55, s55, 0
	s_mov_b32 m0, s70
	v_lshl_add_u64 v[226:227], s[54:55], 0, v[128:129]
	ds_read_b128 v[174:177], v157 offset:32768
	ds_read_b128 v[178:181], v157 offset:33792
	ds_read_b128 v[182:185], v157 offset:34816
	ds_read_b128 v[206:209], v157 offset:35840
	ds_read_b128 v[210:213], v157 offset:36864
	ds_read_b128 v[214:217], v157 offset:37888
	ds_read_b128 v[218:221], v157 offset:38912
	ds_read_b128 v[222:225], v157 offset:39936
	global_load_lds_dwordx4 v[226:227], off
	v_lshl_add_u64 v[226:227], s[54:55], 0, v[130:131]
	s_mov_b32 m0, s71
	s_nop 0
	global_load_lds_dwordx4 v[226:227], off
	s_add_i32 s19, 0, 0x1c000
	v_add_u32_e32 v192, s19, v154
	ds_read_b128 v[226:229], v192
	ds_read_b128 v[230:233], v192 offset:1024
	ds_read_b128 v[234:237], v192 offset:2048
	ds_read_b128 v[238:241], v192 offset:3072
	s_waitcnt vmcnt(8)
	s_waitcnt lgkmcnt(0)
	s_barrier
	s_setprio 1
	v_mfma_f32_16x16x32_bf16 v[124:127], v[158:161], v[174:177], v[124:127]
	v_mfma_f32_16x16x32_bf16 v[120:123], v[166:169], v[174:177], v[120:123]
	v_mfma_f32_16x16x32_bf16 v[116:119], v[158:161], v[182:185], v[116:119]
	v_mfma_f32_16x16x32_bf16 v[112:115], v[166:169], v[182:185], v[112:115]
	v_mfma_f32_16x16x32_bf16 v[108:111], v[158:161], v[210:213], v[108:111]
	v_mfma_f32_16x16x32_bf16 v[104:107], v[166:169], v[210:213], v[104:107]
	v_mfma_f32_16x16x32_bf16 v[100:103], v[158:161], v[218:221], v[100:103]
	v_mfma_f32_16x16x32_bf16 v[96:99], v[166:169], v[218:221], v[96:99]
	v_mfma_f32_16x16x32_bf16 v[124:127], v[162:165], v[178:181], v[124:127]
	v_mfma_f32_16x16x32_bf16 v[120:123], v[170:173], v[178:181], v[120:123]
	v_mfma_f32_16x16x32_bf16 v[116:119], v[162:165], v[206:209], v[116:119]
	v_mfma_f32_16x16x32_bf16 v[112:115], v[170:173], v[206:209], v[112:115]
	v_mfma_f32_16x16x32_bf16 v[108:111], v[162:165], v[214:217], v[108:111]
	v_mfma_f32_16x16x32_bf16 v[104:107], v[170:173], v[214:217], v[104:107]
	v_mfma_f32_16x16x32_bf16 v[100:103], v[162:165], v[222:225], v[100:103]
	v_mfma_f32_16x16x32_bf16 v[96:99], v[170:173], v[222:225], v[96:99]
	v_mfma_f32_16x16x32_bf16 v[92:95], v[226:229], v[174:177], v[92:95]
	v_mfma_f32_16x16x32_bf16 v[88:91], v[234:237], v[174:177], v[88:91]
	v_mfma_f32_16x16x32_bf16 v[84:87], v[226:229], v[182:185], v[84:87]
	v_mfma_f32_16x16x32_bf16 v[80:83], v[234:237], v[182:185], v[80:83]
	v_mfma_f32_16x16x32_bf16 v[76:79], v[226:229], v[210:213], v[76:79]
	v_mfma_f32_16x16x32_bf16 v[72:75], v[234:237], v[210:213], v[72:75]
	v_mfma_f32_16x16x32_bf16 v[68:71], v[226:229], v[218:221], v[68:71]
	v_mfma_f32_16x16x32_bf16 v[64:67], v[234:237], v[218:221], v[64:67]
	v_mfma_f32_16x16x32_bf16 v[92:95], v[230:233], v[178:181], v[92:95]
	v_mfma_f32_16x16x32_bf16 v[88:91], v[238:241], v[178:181], v[88:91]
	v_mfma_f32_16x16x32_bf16 v[84:87], v[230:233], v[206:209], v[84:87]
	v_mfma_f32_16x16x32_bf16 v[80:83], v[238:241], v[206:209], v[80:83]
	v_mfma_f32_16x16x32_bf16 v[76:79], v[230:233], v[214:217], v[76:79]
	v_mfma_f32_16x16x32_bf16 v[72:75], v[238:241], v[214:217], v[72:75]
	v_mfma_f32_16x16x32_bf16 v[68:71], v[230:233], v[222:225], v[68:71]
	v_mfma_f32_16x16x32_bf16 v[64:67], v[238:241], v[222:225], v[64:67]
	s_setprio 0
	s_barrier
	s_add_i32 s6, s6, s59
	v_lshl_add_u64 v[146:147], v[146:147], 0, s[36:37]
	s_mov_b32 m0, s6
	s_nop 0
	global_load_lds_dwordx4 v[146:147], off
	v_lshl_add_u64 v[146:147], v[148:149], 0, s[36:37]
	s_add_i32 m0, s6, 0x2000
	s_nop 0
	global_load_lds_dwordx4 v[146:147], off
	s_mov_b32 m0, s72
	v_lshl_add_u64 v[146:147], v[194:195], 0, s[36:37]
	ds_read_b128 v[174:177], v157 offset:49152
	ds_read_b128 v[178:181], v157 offset:50176
	ds_read_b128 v[182:185], v157 offset:51200
	ds_read_b128 v[206:209], v157 offset:52224
	ds_read_b128 v[210:213], v157 offset:53248
	ds_read_b128 v[214:217], v157 offset:54272
	ds_read_b128 v[218:221], v157 offset:55296
	ds_read_b128 v[222:225], v157 offset:56320
	global_load_lds_dwordx4 v[146:147], off
	v_lshl_add_u64 v[146:147], v[196:197], 0, s[36:37]
	s_mov_b32 m0, s73
	s_nop 0
	global_load_lds_dwordx4 v[146:147], off
	s_add_u32 s52, s52, 0x40080
	s_addc_u32 s53, s53, 0
	s_add_i32 s6, s19, s59
	v_lshl_add_u64 v[146:147], s[52:53], 0, v[140:141]
	s_mov_b32 m0, s6
	s_nop 0
	global_load_lds_dwordx4 v[146:147], off
	v_lshl_add_u64 v[146:147], s[52:53], 0, v[132:133]
	s_add_i32 m0, s6, 0x2000
	s_nop 0
	global_load_lds_dwordx4 v[146:147], off
	s_waitcnt vmcnt(8)
	s_waitcnt lgkmcnt(0)
	s_barrier
	s_setprio 1
	v_mfma_f32_16x16x32_bf16 v[60:63], v[158:161], v[174:177], v[60:63]
	v_mfma_f32_16x16x32_bf16 v[56:59], v[166:169], v[174:177], v[56:59]
	v_mfma_f32_16x16x32_bf16 v[52:55], v[158:161], v[182:185], v[52:55]
	v_mfma_f32_16x16x32_bf16 v[48:51], v[166:169], v[182:185], v[48:51]
	v_mfma_f32_16x16x32_bf16 v[44:47], v[158:161], v[210:213], v[44:47]
	v_mfma_f32_16x16x32_bf16 v[40:43], v[166:169], v[210:213], v[40:43]
	v_mfma_f32_16x16x32_bf16 v[36:39], v[158:161], v[218:221], v[36:39]
	v_mfma_f32_16x16x32_bf16 v[32:35], v[166:169], v[218:221], v[32:35]
	v_mfma_f32_16x16x32_bf16 v[60:63], v[162:165], v[178:181], v[60:63]
	v_mfma_f32_16x16x32_bf16 v[56:59], v[170:173], v[178:181], v[56:59]
	v_mfma_f32_16x16x32_bf16 v[52:55], v[162:165], v[206:209], v[52:55]
	v_mfma_f32_16x16x32_bf16 v[48:51], v[170:173], v[206:209], v[48:51]
	v_mfma_f32_16x16x32_bf16 v[44:47], v[162:165], v[214:217], v[44:47]
	v_mfma_f32_16x16x32_bf16 v[40:43], v[170:173], v[214:217], v[40:43]
	v_mfma_f32_16x16x32_bf16 v[36:39], v[162:165], v[222:225], v[36:39]
	v_mfma_f32_16x16x32_bf16 v[32:35], v[170:173], v[222:225], v[32:35]
	v_mfma_f32_16x16x32_bf16 v[28:31], v[226:229], v[174:177], v[28:31]
	v_mfma_f32_16x16x32_bf16 v[24:27], v[234:237], v[174:177], v[24:27]
	v_mfma_f32_16x16x32_bf16 v[20:23], v[226:229], v[182:185], v[20:23]
	v_mfma_f32_16x16x32_bf16 v[16:19], v[234:237], v[182:185], v[16:19]
	v_mfma_f32_16x16x32_bf16 v[12:15], v[226:229], v[210:213], v[12:15]
	v_mfma_f32_16x16x32_bf16 v[8:11], v[234:237], v[210:213], v[8:11]
	v_mfma_f32_16x16x32_bf16 v[4:7], v[226:229], v[218:221], v[4:7]
	v_mfma_f32_16x16x32_bf16 v[0:3], v[234:237], v[218:221], v[0:3]
	v_mfma_f32_16x16x32_bf16 v[28:31], v[230:233], v[178:181], v[28:31]
	v_mfma_f32_16x16x32_bf16 v[24:27], v[238:241], v[178:181], v[24:27]
	v_mfma_f32_16x16x32_bf16 v[20:23], v[230:233], v[206:209], v[20:23]
	v_mfma_f32_16x16x32_bf16 v[16:19], v[238:241], v[206:209], v[16:19]
	v_mfma_f32_16x16x32_bf16 v[12:15], v[230:233], v[214:217], v[12:15]
	v_mfma_f32_16x16x32_bf16 v[8:11], v[238:241], v[214:217], v[8:11]
	v_mfma_f32_16x16x32_bf16 v[4:7], v[230:233], v[222:225], v[4:7]
	v_mfma_f32_16x16x32_bf16 v[0:3], v[238:241], v[222:225], v[0:3]
	s_setprio 0
	s_add_i32 s81, s81, 2
	s_add_u32 s50, s50, 0x100
	s_addc_u32 s51, s51, 0
	s_cmp_gt_u32 s81, 13
	s_barrier
	s_cbranch_scc0 .LBB0_77
	s_mov_b32 s100, 1
	v_lshl_add_u32 v158, s75, 10, v155
	ds_read2_b32 v[146:147], v158 offset1:16
	s_add_u32 s50, s10, 0xffffff00
	s_addc_u32 s51, s11, -1
	s_ashr_i32 s31, s30, 31
	s_lshl_b64 s[10:11], s[30:31], 8
	s_waitcnt lgkmcnt(0)
	v_mul_f32_e32 v184, 0xbfb8aa3b, v146
	v_mul_f32_e32 v206, v146, v146
	v_pk_mul_f32 v[168:169], v[124:125], v[184:185] op_sel_hi:[1,0]
	v_pk_mul_f32 v[170:171], v[126:127], v[184:185] op_sel_hi:[1,0]
	v_pk_mul_f32 v[172:173], v[120:121], v[184:185] op_sel_hi:[1,0]
	v_pk_mul_f32 v[174:175], v[122:123], v[184:185] op_sel_hi:[1,0]
	v_exp_f32_e32 v168, v168
	v_exp_f32_e32 v169, v169
	v_exp_f32_e32 v170, v170
	v_exp_f32_e32 v171, v171
	v_exp_f32_e32 v172, v172
	v_exp_f32_e32 v173, v173
	v_exp_f32_e32 v174, v174
	v_exp_f32_e32 v175, v175
	v_pk_mul_f32 v[176:177], v[124:125], v[92:93]
	v_pk_mul_f32 v[178:179], v[126:127], v[94:95]
	v_pk_mul_f32 v[180:181], v[120:121], v[88:89]
	v_pk_mul_f32 v[182:183], v[122:123], v[90:91]
	v_pk_add_f32 v[168:169], v[168:169], 1.0 op_sel_hi:[1,0]
	v_pk_add_f32 v[170:171], v[170:171], 1.0 op_sel_hi:[1,0]
	v_pk_add_f32 v[172:173], v[172:173], 1.0 op_sel_hi:[1,0]
	v_pk_add_f32 v[174:175], v[174:175], 1.0 op_sel_hi:[1,0]
	v_rcp_f32_e32 v168, v168
	v_rcp_f32_e32 v169, v169
	v_rcp_f32_e32 v170, v170
	v_rcp_f32_e32 v171, v171
	v_rcp_f32_e32 v172, v172
	v_rcp_f32_e32 v173, v173
	v_rcp_f32_e32 v174, v174
	v_rcp_f32_e32 v175, v175
	v_pk_mul_f32 v[176:177], v[176:177], v[206:207] op_sel_hi:[1,0]
	v_pk_mul_f32 v[178:179], v[178:179], v[206:207] op_sel_hi:[1,0]
	v_pk_mul_f32 v[180:181], v[180:181], v[206:207] op_sel_hi:[1,0]
	v_pk_mul_f32 v[182:183], v[182:183], v[206:207] op_sel_hi:[1,0]
	v_pk_mul_f32 v[176:177], v[176:177], v[168:169]
	v_pk_mul_f32 v[178:179], v[178:179], v[170:171]
	v_pk_mul_f32 v[180:181], v[180:181], v[172:173]
	v_pk_mul_f32 v[182:183], v[182:183], v[174:175]
	v_cvt_pk_bf16_f32 v160, v176, v177
	v_cvt_pk_bf16_f32 v161, v178, v179
	v_cvt_pk_bf16_f32 v162, v180, v181
	v_cvt_pk_bf16_f32 v163, v182, v183
	v_lshl_add_u64 v[152:153], v[134:135], 0, s[10:11]
	s_movk_i32 s6, 0x1600
	v_lshl_or_b32 v150, s74, 7, v156
	v_ashrrev_i32_e32 v151, 31, v150
	s_nop 1
	v_mov_b64_e32 v[148:149], s[28:29]
	v_mad_u64_u32 v[148:149], s[10:11], v152, s6, v[148:149]
	v_mov_b32_e32 v146, v149
	v_mad_u64_u32 v[152:153], s[10:11], v153, s6, v[146:147]
	v_mov_b32_e32 v149, v152
	v_mov_b32_e32 v146, v147
	v_lshl_add_u64 v[150:151], v[150:151], 1, v[148:149]
	global_store_dwordx4 v[150:151], v[160:163], off
	v_mul_f32_e32 v184, 0xbfb8aa3b, v146
	v_mul_f32_e32 v206, v146, v146
	v_pk_mul_f32 v[168:169], v[116:117], v[184:185] op_sel_hi:[1,0]
	v_pk_mul_f32 v[170:171], v[118:119], v[184:185] op_sel_hi:[1,0]
	v_pk_mul_f32 v[172:173], v[112:113], v[184:185] op_sel_hi:[1,0]
	v_pk_mul_f32 v[174:175], v[114:115], v[184:185] op_sel_hi:[1,0]
	v_exp_f32_e32 v168, v168
	v_exp_f32_e32 v169, v169
	v_exp_f32_e32 v170, v170
	v_exp_f32_e32 v171, v171
	v_exp_f32_e32 v172, v172
	v_exp_f32_e32 v173, v173
	v_exp_f32_e32 v174, v174
	v_exp_f32_e32 v175, v175
	v_pk_mul_f32 v[176:177], v[116:117], v[84:85]
	v_pk_mul_f32 v[178:179], v[118:119], v[86:87]
	v_pk_mul_f32 v[180:181], v[112:113], v[80:81]
	v_pk_mul_f32 v[182:183], v[114:115], v[82:83]
	v_pk_add_f32 v[168:169], v[168:169], 1.0 op_sel_hi:[1,0]
	v_pk_add_f32 v[170:171], v[170:171], 1.0 op_sel_hi:[1,0]
	v_pk_add_f32 v[172:173], v[172:173], 1.0 op_sel_hi:[1,0]
	v_pk_add_f32 v[174:175], v[174:175], 1.0 op_sel_hi:[1,0]
	v_rcp_f32_e32 v168, v168
	v_rcp_f32_e32 v169, v169
	v_rcp_f32_e32 v170, v170
	v_rcp_f32_e32 v171, v171
	v_rcp_f32_e32 v172, v172
	v_rcp_f32_e32 v173, v173
	v_rcp_f32_e32 v174, v174
	v_rcp_f32_e32 v175, v175
	v_pk_mul_f32 v[176:177], v[176:177], v[206:207] op_sel_hi:[1,0]
	v_pk_mul_f32 v[178:179], v[178:179], v[206:207] op_sel_hi:[1,0]
	v_pk_mul_f32 v[180:181], v[180:181], v[206:207] op_sel_hi:[1,0]
	v_pk_mul_f32 v[182:183], v[182:183], v[206:207] op_sel_hi:[1,0]
	v_pk_mul_f32 v[176:177], v[176:177], v[168:169]
	v_pk_mul_f32 v[178:179], v[178:179], v[170:171]
	v_pk_mul_f32 v[180:181], v[180:181], v[172:173]
	v_pk_mul_f32 v[182:183], v[182:183], v[174:175]
	v_cvt_pk_bf16_f32 v160, v176, v177
	v_cvt_pk_bf16_f32 v161, v178, v179
	v_cvt_pk_bf16_f32 v162, v180, v181
	v_cvt_pk_bf16_f32 v163, v182, v183
	s_mov_b32 s6, 0x16000
	s_nop 1
	v_add_co_u32_e32 v146, vcc, s6, v150
	s_nop 0
	v_addc_co_u32_e32 v147, vcc, 0, v151, vcc
	global_store_dwordx4 v[146:147], v[160:163], off
	ds_read2_b32 v[146:147], v158 offset0:32 offset1:48
	s_mov_b32 s6, 0x2c000
	s_waitcnt lgkmcnt(0)
	v_mul_f32_e32 v184, 0xbfb8aa3b, v146
	v_mul_f32_e32 v206, v146, v146
	v_pk_mul_f32 v[168:169], v[108:109], v[184:185] op_sel_hi:[1,0]
	v_pk_mul_f32 v[170:171], v[110:111], v[184:185] op_sel_hi:[1,0]
	v_pk_mul_f32 v[172:173], v[104:105], v[184:185] op_sel_hi:[1,0]
	v_pk_mul_f32 v[174:175], v[106:107], v[184:185] op_sel_hi:[1,0]
	v_exp_f32_e32 v168, v168
	v_exp_f32_e32 v169, v169
	v_exp_f32_e32 v170, v170
	v_exp_f32_e32 v171, v171
	v_exp_f32_e32 v172, v172
	v_exp_f32_e32 v173, v173
	v_exp_f32_e32 v174, v174
	v_exp_f32_e32 v175, v175
	v_pk_mul_f32 v[176:177], v[108:109], v[76:77]
	v_pk_mul_f32 v[178:179], v[110:111], v[78:79]
	v_pk_mul_f32 v[180:181], v[104:105], v[72:73]
	v_pk_mul_f32 v[182:183], v[106:107], v[74:75]
	v_pk_add_f32 v[168:169], v[168:169], 1.0 op_sel_hi:[1,0]
	v_pk_add_f32 v[170:171], v[170:171], 1.0 op_sel_hi:[1,0]
	v_pk_add_f32 v[172:173], v[172:173], 1.0 op_sel_hi:[1,0]
	v_pk_add_f32 v[174:175], v[174:175], 1.0 op_sel_hi:[1,0]
	v_rcp_f32_e32 v168, v168
	v_rcp_f32_e32 v169, v169
	v_rcp_f32_e32 v170, v170
	v_rcp_f32_e32 v171, v171
	v_rcp_f32_e32 v172, v172
	v_rcp_f32_e32 v173, v173
	v_rcp_f32_e32 v174, v174
	v_rcp_f32_e32 v175, v175
	v_pk_mul_f32 v[176:177], v[176:177], v[206:207] op_sel_hi:[1,0]
	v_pk_mul_f32 v[178:179], v[178:179], v[206:207] op_sel_hi:[1,0]
	v_pk_mul_f32 v[180:181], v[180:181], v[206:207] op_sel_hi:[1,0]
	v_pk_mul_f32 v[182:183], v[182:183], v[206:207] op_sel_hi:[1,0]
	v_pk_mul_f32 v[176:177], v[176:177], v[168:169]
	v_pk_mul_f32 v[178:179], v[178:179], v[170:171]
	v_pk_mul_f32 v[180:181], v[180:181], v[172:173]
	v_pk_mul_f32 v[182:183], v[182:183], v[174:175]
	v_cvt_pk_bf16_f32 v160, v176, v177
	v_cvt_pk_bf16_f32 v161, v178, v179
	v_cvt_pk_bf16_f32 v162, v180, v181
	v_cvt_pk_bf16_f32 v163, v182, v183
	s_nop 1
	v_mov_b32_e32 v146, v147
	v_add_co_u32_e32 v148, vcc, s6, v150
	v_addc_co_u32_e32 v149, vcc, 0, v151, vcc
	global_store_dwordx4 v[148:149], v[160:163], off
	v_mul_f32_e32 v184, 0xbfb8aa3b, v146
	v_mul_f32_e32 v206, v146, v146
	v_pk_mul_f32 v[168:169], v[100:101], v[184:185] op_sel_hi:[1,0]
	v_pk_mul_f32 v[170:171], v[102:103], v[184:185] op_sel_hi:[1,0]
	v_pk_mul_f32 v[172:173], v[96:97], v[184:185] op_sel_hi:[1,0]
	v_pk_mul_f32 v[174:175], v[98:99], v[184:185] op_sel_hi:[1,0]
	v_exp_f32_e32 v168, v168
	v_exp_f32_e32 v169, v169
	v_exp_f32_e32 v170, v170
	v_exp_f32_e32 v171, v171
	v_exp_f32_e32 v172, v172
	v_exp_f32_e32 v173, v173
	v_exp_f32_e32 v174, v174
	v_exp_f32_e32 v175, v175
	v_pk_mul_f32 v[176:177], v[100:101], v[68:69]
	v_pk_mul_f32 v[178:179], v[102:103], v[70:71]
	v_pk_mul_f32 v[180:181], v[96:97], v[64:65]
	v_pk_mul_f32 v[182:183], v[98:99], v[66:67]
	v_pk_add_f32 v[168:169], v[168:169], 1.0 op_sel_hi:[1,0]
	v_pk_add_f32 v[170:171], v[170:171], 1.0 op_sel_hi:[1,0]
	v_pk_add_f32 v[172:173], v[172:173], 1.0 op_sel_hi:[1,0]
	v_pk_add_f32 v[174:175], v[174:175], 1.0 op_sel_hi:[1,0]
	v_rcp_f32_e32 v168, v168
	v_rcp_f32_e32 v169, v169
	v_rcp_f32_e32 v170, v170
	v_rcp_f32_e32 v171, v171
	v_rcp_f32_e32 v172, v172
	v_rcp_f32_e32 v173, v173
	v_rcp_f32_e32 v174, v174
	v_rcp_f32_e32 v175, v175
	v_pk_mul_f32 v[176:177], v[176:177], v[206:207] op_sel_hi:[1,0]
	v_pk_mul_f32 v[178:179], v[178:179], v[206:207] op_sel_hi:[1,0]
	v_pk_mul_f32 v[180:181], v[180:181], v[206:207] op_sel_hi:[1,0]
	v_pk_mul_f32 v[182:183], v[182:183], v[206:207] op_sel_hi:[1,0]
	v_pk_mul_f32 v[176:177], v[176:177], v[168:169]
	v_pk_mul_f32 v[178:179], v[178:179], v[170:171]
	v_pk_mul_f32 v[180:181], v[180:181], v[172:173]
	v_pk_mul_f32 v[182:183], v[182:183], v[174:175]
	v_cvt_pk_bf16_f32 v160, v176, v177
	v_cvt_pk_bf16_f32 v161, v178, v179
	v_cvt_pk_bf16_f32 v162, v180, v181
	v_cvt_pk_bf16_f32 v163, v182, v183
	s_mov_b32 s6, 0x42000
	s_nop 1
	v_add_co_u32_e32 v146, vcc, s6, v150
	s_nop 0
	v_addc_co_u32_e32 v147, vcc, 0, v151, vcc
	global_store_dwordx4 v[146:147], v[160:163], off
	ds_read2_b32 v[146:147], v158 offset0:128 offset1:144
	s_mov_b32 s6, 0xb0000
	s_waitcnt lgkmcnt(0)
	v_mul_f32_e32 v184, 0xbfb8aa3b, v146
	v_mul_f32_e32 v206, v146, v146
	v_pk_mul_f32 v[168:169], v[60:61], v[184:185] op_sel_hi:[1,0]
	v_pk_mul_f32 v[170:171], v[62:63], v[184:185] op_sel_hi:[1,0]
	v_pk_mul_f32 v[172:173], v[56:57], v[184:185] op_sel_hi:[1,0]
	v_pk_mul_f32 v[174:175], v[58:59], v[184:185] op_sel_hi:[1,0]
	v_exp_f32_e32 v168, v168
	v_exp_f32_e32 v169, v169
	v_exp_f32_e32 v170, v170
	v_exp_f32_e32 v171, v171
	v_exp_f32_e32 v172, v172
	v_exp_f32_e32 v173, v173
	v_exp_f32_e32 v174, v174
	v_exp_f32_e32 v175, v175
	v_pk_mul_f32 v[176:177], v[60:61], v[28:29]
	v_pk_mul_f32 v[178:179], v[62:63], v[30:31]
	v_pk_mul_f32 v[180:181], v[56:57], v[24:25]
	v_pk_mul_f32 v[182:183], v[58:59], v[26:27]
	v_pk_add_f32 v[168:169], v[168:169], 1.0 op_sel_hi:[1,0]
	v_pk_add_f32 v[170:171], v[170:171], 1.0 op_sel_hi:[1,0]
	v_pk_add_f32 v[172:173], v[172:173], 1.0 op_sel_hi:[1,0]
	v_pk_add_f32 v[174:175], v[174:175], 1.0 op_sel_hi:[1,0]
	v_rcp_f32_e32 v168, v168
	v_rcp_f32_e32 v169, v169
	v_rcp_f32_e32 v170, v170
	v_rcp_f32_e32 v171, v171
	v_rcp_f32_e32 v172, v172
	v_rcp_f32_e32 v173, v173
	v_rcp_f32_e32 v174, v174
	v_rcp_f32_e32 v175, v175
	v_pk_mul_f32 v[176:177], v[176:177], v[206:207] op_sel_hi:[1,0]
	v_pk_mul_f32 v[178:179], v[178:179], v[206:207] op_sel_hi:[1,0]
	v_pk_mul_f32 v[180:181], v[180:181], v[206:207] op_sel_hi:[1,0]
	v_pk_mul_f32 v[182:183], v[182:183], v[206:207] op_sel_hi:[1,0]
	v_pk_mul_f32 v[176:177], v[176:177], v[168:169]
	v_pk_mul_f32 v[178:179], v[178:179], v[170:171]
	v_pk_mul_f32 v[180:181], v[180:181], v[172:173]
	v_pk_mul_f32 v[182:183], v[182:183], v[174:175]
	v_cvt_pk_bf16_f32 v160, v176, v177
	v_cvt_pk_bf16_f32 v161, v178, v179
	v_cvt_pk_bf16_f32 v162, v180, v181
	v_cvt_pk_bf16_f32 v163, v182, v183
	s_nop 1
	v_mov_b32_e32 v146, v147
	v_add_co_u32_e32 v148, vcc, s6, v150
	v_addc_co_u32_e32 v149, vcc, 0, v151, vcc
	global_store_dwordx4 v[148:149], v[160:163], off
	v_mul_f32_e32 v184, 0xbfb8aa3b, v146
	v_mul_f32_e32 v206, v146, v146
	v_pk_mul_f32 v[168:169], v[52:53], v[184:185] op_sel_hi:[1,0]
	v_pk_mul_f32 v[170:171], v[54:55], v[184:185] op_sel_hi:[1,0]
	v_pk_mul_f32 v[172:173], v[48:49], v[184:185] op_sel_hi:[1,0]
	v_pk_mul_f32 v[174:175], v[50:51], v[184:185] op_sel_hi:[1,0]
	v_exp_f32_e32 v168, v168
	v_exp_f32_e32 v169, v169
	v_exp_f32_e32 v170, v170
	v_exp_f32_e32 v171, v171
	v_exp_f32_e32 v172, v172
	v_exp_f32_e32 v173, v173
	v_exp_f32_e32 v174, v174
	v_exp_f32_e32 v175, v175
	v_pk_mul_f32 v[176:177], v[52:53], v[20:21]
	v_pk_mul_f32 v[178:179], v[54:55], v[22:23]
	v_pk_mul_f32 v[180:181], v[48:49], v[16:17]
	v_pk_mul_f32 v[182:183], v[50:51], v[18:19]
	v_pk_add_f32 v[168:169], v[168:169], 1.0 op_sel_hi:[1,0]
	v_pk_add_f32 v[170:171], v[170:171], 1.0 op_sel_hi:[1,0]
	v_pk_add_f32 v[172:173], v[172:173], 1.0 op_sel_hi:[1,0]
	v_pk_add_f32 v[174:175], v[174:175], 1.0 op_sel_hi:[1,0]
	v_rcp_f32_e32 v168, v168
	v_rcp_f32_e32 v169, v169
	v_rcp_f32_e32 v170, v170
	v_rcp_f32_e32 v171, v171
	v_rcp_f32_e32 v172, v172
	v_rcp_f32_e32 v173, v173
	v_rcp_f32_e32 v174, v174
	v_rcp_f32_e32 v175, v175
	v_pk_mul_f32 v[176:177], v[176:177], v[206:207] op_sel_hi:[1,0]
	v_pk_mul_f32 v[178:179], v[178:179], v[206:207] op_sel_hi:[1,0]
	v_pk_mul_f32 v[180:181], v[180:181], v[206:207] op_sel_hi:[1,0]
	v_pk_mul_f32 v[182:183], v[182:183], v[206:207] op_sel_hi:[1,0]
	v_pk_mul_f32 v[176:177], v[176:177], v[168:169]
	v_pk_mul_f32 v[178:179], v[178:179], v[170:171]
	v_pk_mul_f32 v[180:181], v[180:181], v[172:173]
	v_pk_mul_f32 v[182:183], v[182:183], v[174:175]
	v_cvt_pk_bf16_f32 v160, v176, v177
	v_cvt_pk_bf16_f32 v161, v178, v179
	v_cvt_pk_bf16_f32 v162, v180, v181
	v_cvt_pk_bf16_f32 v163, v182, v183
	s_mov_b32 s6, 0xc6000
	s_nop 1
	v_add_co_u32_e32 v146, vcc, s6, v150
	s_nop 0
	v_addc_co_u32_e32 v147, vcc, 0, v151, vcc
	global_store_dwordx4 v[146:147], v[160:163], off
	ds_read2_b32 v[146:147], v158 offset0:160 offset1:176
	s_mov_b32 s6, 0xdc000
	s_waitcnt lgkmcnt(0)
	v_mul_f32_e32 v184, 0xbfb8aa3b, v146
	v_mul_f32_e32 v206, v146, v146
	v_pk_mul_f32 v[168:169], v[44:45], v[184:185] op_sel_hi:[1,0]
	v_pk_mul_f32 v[170:171], v[46:47], v[184:185] op_sel_hi:[1,0]
	v_pk_mul_f32 v[172:173], v[40:41], v[184:185] op_sel_hi:[1,0]
	v_pk_mul_f32 v[174:175], v[42:43], v[184:185] op_sel_hi:[1,0]
	v_exp_f32_e32 v168, v168
	v_exp_f32_e32 v169, v169
	v_exp_f32_e32 v170, v170
	v_exp_f32_e32 v171, v171
	v_exp_f32_e32 v172, v172
	v_exp_f32_e32 v173, v173
	v_exp_f32_e32 v174, v174
	v_exp_f32_e32 v175, v175
	v_pk_mul_f32 v[176:177], v[44:45], v[12:13]
	v_pk_mul_f32 v[178:179], v[46:47], v[14:15]
	v_pk_mul_f32 v[180:181], v[40:41], v[8:9]
	v_pk_mul_f32 v[182:183], v[42:43], v[10:11]
	v_pk_add_f32 v[168:169], v[168:169], 1.0 op_sel_hi:[1,0]
	v_pk_add_f32 v[170:171], v[170:171], 1.0 op_sel_hi:[1,0]
	v_pk_add_f32 v[172:173], v[172:173], 1.0 op_sel_hi:[1,0]
	v_pk_add_f32 v[174:175], v[174:175], 1.0 op_sel_hi:[1,0]
	v_rcp_f32_e32 v168, v168
	v_rcp_f32_e32 v169, v169
	v_rcp_f32_e32 v170, v170
	v_rcp_f32_e32 v171, v171
	v_rcp_f32_e32 v172, v172
	v_rcp_f32_e32 v173, v173
	v_rcp_f32_e32 v174, v174
	v_rcp_f32_e32 v175, v175
	v_pk_mul_f32 v[176:177], v[176:177], v[206:207] op_sel_hi:[1,0]
	v_pk_mul_f32 v[178:179], v[178:179], v[206:207] op_sel_hi:[1,0]
	v_pk_mul_f32 v[180:181], v[180:181], v[206:207] op_sel_hi:[1,0]
	v_pk_mul_f32 v[182:183], v[182:183], v[206:207] op_sel_hi:[1,0]
	v_pk_mul_f32 v[176:177], v[176:177], v[168:169]
	v_pk_mul_f32 v[178:179], v[178:179], v[170:171]
	v_pk_mul_f32 v[180:181], v[180:181], v[172:173]
	v_pk_mul_f32 v[182:183], v[182:183], v[174:175]
	v_cvt_pk_bf16_f32 v158, v176, v177
	v_cvt_pk_bf16_f32 v159, v178, v179
	v_cvt_pk_bf16_f32 v160, v180, v181
	v_cvt_pk_bf16_f32 v161, v182, v183
	s_nop 1
	v_mov_b32_e32 v146, v147
	v_add_co_u32_e32 v148, vcc, s6, v150
	v_addc_co_u32_e32 v149, vcc, 0, v151, vcc
	global_store_dwordx4 v[148:149], v[158:161], off
	v_mul_f32_e32 v184, 0xbfb8aa3b, v146
	v_mul_f32_e32 v206, v146, v146
	v_pk_mul_f32 v[168:169], v[36:37], v[184:185] op_sel_hi:[1,0]
	v_pk_mul_f32 v[170:171], v[38:39], v[184:185] op_sel_hi:[1,0]
	v_pk_mul_f32 v[172:173], v[32:33], v[184:185] op_sel_hi:[1,0]
	v_pk_mul_f32 v[174:175], v[34:35], v[184:185] op_sel_hi:[1,0]
	v_exp_f32_e32 v168, v168
	v_exp_f32_e32 v169, v169
	v_exp_f32_e32 v170, v170
	v_exp_f32_e32 v171, v171
	v_exp_f32_e32 v172, v172
	v_exp_f32_e32 v173, v173
	v_exp_f32_e32 v174, v174
	v_exp_f32_e32 v175, v175
	v_pk_mul_f32 v[176:177], v[36:37], v[4:5]
	v_pk_mul_f32 v[178:179], v[38:39], v[6:7]
	v_pk_mul_f32 v[180:181], v[32:33], v[0:1]
	v_pk_mul_f32 v[182:183], v[34:35], v[2:3]
	v_pk_add_f32 v[168:169], v[168:169], 1.0 op_sel_hi:[1,0]
	v_pk_add_f32 v[170:171], v[170:171], 1.0 op_sel_hi:[1,0]
	v_pk_add_f32 v[172:173], v[172:173], 1.0 op_sel_hi:[1,0]
	v_pk_add_f32 v[174:175], v[174:175], 1.0 op_sel_hi:[1,0]
	v_rcp_f32_e32 v168, v168
	v_rcp_f32_e32 v169, v169
	v_rcp_f32_e32 v170, v170
	v_rcp_f32_e32 v171, v171
	v_rcp_f32_e32 v172, v172
	v_rcp_f32_e32 v173, v173
	v_rcp_f32_e32 v174, v174
	v_rcp_f32_e32 v175, v175
	v_pk_mul_f32 v[176:177], v[176:177], v[206:207] op_sel_hi:[1,0]
	v_pk_mul_f32 v[178:179], v[178:179], v[206:207] op_sel_hi:[1,0]
	v_pk_mul_f32 v[180:181], v[180:181], v[206:207] op_sel_hi:[1,0]
	v_pk_mul_f32 v[182:183], v[182:183], v[206:207] op_sel_hi:[1,0]
	v_pk_mul_f32 v[176:177], v[176:177], v[168:169]
	v_pk_mul_f32 v[178:179], v[178:179], v[170:171]
	v_pk_mul_f32 v[180:181], v[180:181], v[172:173]
	v_pk_mul_f32 v[182:183], v[182:183], v[174:175]
	v_cvt_pk_bf16_f32 v158, v176, v177
	v_cvt_pk_bf16_f32 v159, v178, v179
	v_cvt_pk_bf16_f32 v160, v180, v181
	v_cvt_pk_bf16_f32 v161, v182, v183
	s_nop 1
	v_add_co_u32_e32 v146, vcc, 0xf2000, v150
	s_nop 0
	v_addc_co_u32_e32 v147, vcc, 0, v151, vcc
	s_andn2_b64 vcc, exec, s[44:45]
	global_store_dwordx4 v[146:147], v[158:161], off
	s_cbranch_vccz .LBB0_73
	s_mov_b64 s[46:47], s[50:51]
	s_andn2_b64 vcc, exec, s[42:43]
	s_mov_b64 s[50:51], s[46:47]
	s_cbranch_vccnz .LBB0_74

.LBB0_386:
	s_add_u32 s6, s28, s52
	s_addc_u32 s19, s29, s53
	s_add_u32 s6, s6, 0x100
	s_addc_u32 s19, s19, 0
	s_add_u32 s23, s10, s52
	s_addc_u32 s54, s11, s53
	s_add_i32 s82, 0, 0x10000
	v_add_u32_e32 v146, s82, v154
	ds_read_b128 v[158:161], v146
	ds_read_b128 v[162:165], v146 offset:1024
	ds_read_b128 v[166:169], v146 offset:2048
	ds_read_b128 v[170:173], v146 offset:3072
	s_cmpk_eq_i32 s52, 0x700
	s_cselect_b32 s59, s12, s19
	s_cselect_b32 s58, s35, s6
	s_cselect_b32 s55, s39, s54
	s_cselect_b32 s54, s47, s23
	v_lshl_add_u64 v[146:147], v[150:151], 0, s[52:53]
	s_add_i32 m0, s68, 0xc000
	ds_read_b128 v[174:177], v157
	ds_read_b128 v[178:181], v157 offset:1024
	ds_read_b128 v[182:185], v157 offset:2048
	ds_read_b128 v[206:209], v157 offset:3072
	ds_read_b128 v[210:213], v157 offset:4096
	ds_read_b128 v[214:217], v157 offset:5120
	ds_read_b128 v[218:221], v157 offset:6144
	ds_read_b128 v[222:225], v157 offset:7168
	global_load_lds_dwordx4 v[146:147], off
	v_lshl_add_u64 v[146:147], v[152:153], 0, s[52:53]
	s_add_i32 m0, s68, 0xe000
	s_nop 0
	global_load_lds_dwordx4 v[146:147], off
	s_add_i32 s6, 0, 0x14000
	v_add_u32_e32 v146, s6, v154
	ds_read_b128 v[226:229], v146
	ds_read_b128 v[230:233], v146 offset:1024
	ds_read_b128 v[234:237], v146 offset:2048
	ds_read_b128 v[238:241], v146 offset:3072
	s_waitcnt vmcnt(8)
	s_waitcnt lgkmcnt(0)
	s_barrier
	s_setprio 1
	v_mfma_f32_16x16x32_bf16 v[124:127], v[158:161], v[174:177], v[124:127]
	v_mfma_f32_16x16x32_bf16 v[120:123], v[166:169], v[174:177], v[120:123]
	v_mfma_f32_16x16x32_bf16 v[116:119], v[158:161], v[182:185], v[116:119]
	v_mfma_f32_16x16x32_bf16 v[112:115], v[166:169], v[182:185], v[112:115]
	v_mfma_f32_16x16x32_bf16 v[108:111], v[158:161], v[210:213], v[108:111]
	v_mfma_f32_16x16x32_bf16 v[104:107], v[166:169], v[210:213], v[104:107]
	v_mfma_f32_16x16x32_bf16 v[100:103], v[158:161], v[218:221], v[100:103]
	v_mfma_f32_16x16x32_bf16 v[96:99], v[166:169], v[218:221], v[96:99]
	v_mfma_f32_16x16x32_bf16 v[124:127], v[162:165], v[178:181], v[124:127]
	v_mfma_f32_16x16x32_bf16 v[120:123], v[170:173], v[178:181], v[120:123]
	v_mfma_f32_16x16x32_bf16 v[116:119], v[162:165], v[206:209], v[116:119]
	v_mfma_f32_16x16x32_bf16 v[112:115], v[170:173], v[206:209], v[112:115]
	v_mfma_f32_16x16x32_bf16 v[108:111], v[162:165], v[214:217], v[108:111]
	v_mfma_f32_16x16x32_bf16 v[104:107], v[170:173], v[214:217], v[104:107]
	v_mfma_f32_16x16x32_bf16 v[100:103], v[162:165], v[222:225], v[100:103]
	v_mfma_f32_16x16x32_bf16 v[96:99], v[170:173], v[222:225], v[96:99]
	v_mfma_f32_16x16x32_bf16 v[92:95], v[226:229], v[174:177], v[92:95]
	v_mfma_f32_16x16x32_bf16 v[88:91], v[234:237], v[174:177], v[88:91]
	v_mfma_f32_16x16x32_bf16 v[84:87], v[226:229], v[182:185], v[84:87]
	v_mfma_f32_16x16x32_bf16 v[80:83], v[234:237], v[182:185], v[80:83]
	v_mfma_f32_16x16x32_bf16 v[76:79], v[226:229], v[210:213], v[76:79]
	v_mfma_f32_16x16x32_bf16 v[72:75], v[234:237], v[210:213], v[72:75]
	v_mfma_f32_16x16x32_bf16 v[68:71], v[226:229], v[218:221], v[68:71]
	v_mfma_f32_16x16x32_bf16 v[64:67], v[234:237], v[218:221], v[64:67]
	v_mfma_f32_16x16x32_bf16 v[92:95], v[230:233], v[178:181], v[92:95]
	v_mfma_f32_16x16x32_bf16 v[88:91], v[238:241], v[178:181], v[88:91]
	v_mfma_f32_16x16x32_bf16 v[84:87], v[230:233], v[206:209], v[84:87]
	v_mfma_f32_16x16x32_bf16 v[80:83], v[238:241], v[206:209], v[80:83]
	v_mfma_f32_16x16x32_bf16 v[76:79], v[230:233], v[214:217], v[76:79]
	v_mfma_f32_16x16x32_bf16 v[72:75], v[238:241], v[214:217], v[72:75]
	v_mfma_f32_16x16x32_bf16 v[68:71], v[230:233], v[222:225], v[68:71]
	v_mfma_f32_16x16x32_bf16 v[64:67], v[238:241], v[222:225], v[64:67]
	s_setprio 0
	s_barrier
	s_add_i32 s19, s82, s57
	v_lshl_add_u64 v[146:147], s[54:55], 0, v[140:141]
	s_mov_b32 m0, s19
	v_lshl_add_u64 v[148:149], s[54:55], 0, v[132:133]
	global_load_lds_dwordx4 v[146:147], off
	s_add_i32 m0, s19, 0x2000
	s_nop 0
	global_load_lds_dwordx4 v[148:149], off
	s_mov_b32 m0, s68
	v_lshl_add_u64 v[194:195], s[58:59], 0, v[128:129]
	ds_read_b128 v[174:177], v157 offset:16384
	ds_read_b128 v[178:181], v157 offset:17408
	ds_read_b128 v[182:185], v157 offset:18432
	ds_read_b128 v[206:209], v157 offset:19456
	ds_read_b128 v[210:213], v157 offset:20480
	ds_read_b128 v[214:217], v157 offset:21504
	ds_read_b128 v[218:221], v157 offset:22528
	ds_read_b128 v[222:225], v157 offset:23552
	global_load_lds_dwordx4 v[194:195], off
	v_lshl_add_u64 v[196:197], s[58:59], 0, v[130:131]
	s_mov_b32 m0, s69
	s_nop 0
	global_load_lds_dwordx4 v[196:197], off
	s_add_u32 s82, s54, 0x40000
	s_addc_u32 s83, s55, 0
	s_add_i32 s6, s6, s57
	v_lshl_add_u64 v[250:251], s[82:83], 0, v[140:141]
	s_mov_b32 m0, s6
	s_nop 0
	global_load_lds_dwordx4 v[250:251], off
	v_lshl_add_u64 v[250:251], s[82:83], 0, v[132:133]
	s_add_i32 m0, s6, 0x2000
	s_nop 0
	global_load_lds_dwordx4 v[250:251], off
	s_waitcnt vmcnt(8)
	s_waitcnt lgkmcnt(0)
	s_barrier
	s_setprio 1
	v_mfma_f32_16x16x32_bf16 v[60:63], v[158:161], v[174:177], v[60:63]
	v_mfma_f32_16x16x32_bf16 v[56:59], v[166:169], v[174:177], v[56:59]
	v_mfma_f32_16x16x32_bf16 v[52:55], v[158:161], v[182:185], v[52:55]
	v_mfma_f32_16x16x32_bf16 v[48:51], v[166:169], v[182:185], v[48:51]
	v_mfma_f32_16x16x32_bf16 v[44:47], v[158:161], v[210:213], v[44:47]
	v_mfma_f32_16x16x32_bf16 v[40:43], v[166:169], v[210:213], v[40:43]
	v_mfma_f32_16x16x32_bf16 v[36:39], v[158:161], v[218:221], v[36:39]
	v_mfma_f32_16x16x32_bf16 v[32:35], v[166:169], v[218:221], v[32:35]
	v_mfma_f32_16x16x32_bf16 v[60:63], v[162:165], v[178:181], v[60:63]
	v_mfma_f32_16x16x32_bf16 v[56:59], v[170:173], v[178:181], v[56:59]
	v_mfma_f32_16x16x32_bf16 v[52:55], v[162:165], v[206:209], v[52:55]
	v_mfma_f32_16x16x32_bf16 v[48:51], v[170:173], v[206:209], v[48:51]
	v_mfma_f32_16x16x32_bf16 v[44:47], v[162:165], v[214:217], v[44:47]
	v_mfma_f32_16x16x32_bf16 v[40:43], v[170:173], v[214:217], v[40:43]
	v_mfma_f32_16x16x32_bf16 v[36:39], v[162:165], v[222:225], v[36:39]
	v_mfma_f32_16x16x32_bf16 v[32:35], v[170:173], v[222:225], v[32:35]
	v_mfma_f32_16x16x32_bf16 v[28:31], v[226:229], v[174:177], v[28:31]
	v_mfma_f32_16x16x32_bf16 v[24:27], v[234:237], v[174:177], v[24:27]
	v_mfma_f32_16x16x32_bf16 v[20:23], v[226:229], v[182:185], v[20:23]
	v_mfma_f32_16x16x32_bf16 v[16:19], v[234:237], v[182:185], v[16:19]
	v_mfma_f32_16x16x32_bf16 v[12:15], v[226:229], v[210:213], v[12:15]
	v_mfma_f32_16x16x32_bf16 v[8:11], v[234:237], v[210:213], v[8:11]
	v_mfma_f32_16x16x32_bf16 v[4:7], v[226:229], v[218:221], v[4:7]
	v_mfma_f32_16x16x32_bf16 v[0:3], v[234:237], v[218:221], v[0:3]
	v_mfma_f32_16x16x32_bf16 v[28:31], v[230:233], v[178:181], v[28:31]
	v_mfma_f32_16x16x32_bf16 v[24:27], v[238:241], v[178:181], v[24:27]
	v_mfma_f32_16x16x32_bf16 v[20:23], v[230:233], v[206:209], v[20:23]
	v_mfma_f32_16x16x32_bf16 v[16:19], v[238:241], v[206:209], v[16:19]
	v_mfma_f32_16x16x32_bf16 v[12:15], v[230:233], v[214:217], v[12:15]
	v_mfma_f32_16x16x32_bf16 v[8:11], v[238:241], v[214:217], v[8:11]
	v_mfma_f32_16x16x32_bf16 v[4:7], v[230:233], v[222:225], v[4:7]
	v_mfma_f32_16x16x32_bf16 v[0:3], v[238:241], v[222:225], v[0:3]
	s_setprio 0
	s_barrier
	s_add_i32 s6, 0, 0x18000
	v_add_u32_e32 v170, s6, v154
	ds_read_b128 v[158:161], v170
	ds_read_b128 v[162:165], v170 offset:1024
	ds_read_b128 v[166:169], v170 offset:2048
	ds_read_b128 v[170:173], v170 offset:3072
	s_add_u32 s58, s58, 0x40000
	s_addc_u32 s59, s59, 0
	s_mov_b32 m0, s70
	v_lshl_add_u64 v[226:227], s[58:59], 0, v[128:129]
	ds_read_b128 v[174:177], v157 offset:32768
	ds_read_b128 v[178:181], v157 offset:33792
	ds_read_b128 v[182:185], v157 offset:34816
	ds_read_b128 v[206:209], v157 offset:35840
	ds_read_b128 v[210:213], v157 offset:36864
	ds_read_b128 v[214:217], v157 offset:37888
	ds_read_b128 v[218:221], v157 offset:38912
	ds_read_b128 v[222:225], v157 offset:39936
	global_load_lds_dwordx4 v[226:227], off
	v_lshl_add_u64 v[226:227], s[58:59], 0, v[130:131]
	s_mov_b32 m0, s71
	s_nop 0
	global_load_lds_dwordx4 v[226:227], off
	s_add_i32 s19, 0, 0x1c000
	v_add_u32_e32 v192, s19, v154
	ds_read_b128 v[226:229], v192
	ds_read_b128 v[230:233], v192 offset:1024
	ds_read_b128 v[234:237], v192 offset:2048
	ds_read_b128 v[238:241], v192 offset:3072
	s_waitcnt vmcnt(8)
	s_waitcnt lgkmcnt(0)
	s_barrier
	s_setprio 1
	v_mfma_f32_16x16x32_bf16 v[124:127], v[158:161], v[174:177], v[124:127]
	v_mfma_f32_16x16x32_bf16 v[120:123], v[166:169], v[174:177], v[120:123]
	v_mfma_f32_16x16x32_bf16 v[116:119], v[158:161], v[182:185], v[116:119]
	v_mfma_f32_16x16x32_bf16 v[112:115], v[166:169], v[182:185], v[112:115]
	v_mfma_f32_16x16x32_bf16 v[108:111], v[158:161], v[210:213], v[108:111]
	v_mfma_f32_16x16x32_bf16 v[104:107], v[166:169], v[210:213], v[104:107]
	v_mfma_f32_16x16x32_bf16 v[100:103], v[158:161], v[218:221], v[100:103]
	v_mfma_f32_16x16x32_bf16 v[96:99], v[166:169], v[218:221], v[96:99]
	v_mfma_f32_16x16x32_bf16 v[124:127], v[162:165], v[178:181], v[124:127]
	v_mfma_f32_16x16x32_bf16 v[120:123], v[170:173], v[178:181], v[120:123]
	v_mfma_f32_16x16x32_bf16 v[116:119], v[162:165], v[206:209], v[116:119]
	v_mfma_f32_16x16x32_bf16 v[112:115], v[170:173], v[206:209], v[112:115]
	v_mfma_f32_16x16x32_bf16 v[108:111], v[162:165], v[214:217], v[108:111]
	v_mfma_f32_16x16x32_bf16 v[104:107], v[170:173], v[214:217], v[104:107]
	v_mfma_f32_16x16x32_bf16 v[100:103], v[162:165], v[222:225], v[100:103]
	v_mfma_f32_16x16x32_bf16 v[96:99], v[170:173], v[222:225], v[96:99]
	v_mfma_f32_16x16x32_bf16 v[92:95], v[226:229], v[174:177], v[92:95]
	v_mfma_f32_16x16x32_bf16 v[88:91], v[234:237], v[174:177], v[88:91]
	v_mfma_f32_16x16x32_bf16 v[84:87], v[226:229], v[182:185], v[84:87]
	v_mfma_f32_16x16x32_bf16 v[80:83], v[234:237], v[182:185], v[80:83]
	v_mfma_f32_16x16x32_bf16 v[76:79], v[226:229], v[210:213], v[76:79]
	v_mfma_f32_16x16x32_bf16 v[72:75], v[234:237], v[210:213], v[72:75]
	v_mfma_f32_16x16x32_bf16 v[68:71], v[226:229], v[218:221], v[68:71]
	v_mfma_f32_16x16x32_bf16 v[64:67], v[234:237], v[218:221], v[64:67]
	v_mfma_f32_16x16x32_bf16 v[92:95], v[230:233], v[178:181], v[92:95]
	v_mfma_f32_16x16x32_bf16 v[88:91], v[238:241], v[178:181], v[88:91]
	v_mfma_f32_16x16x32_bf16 v[84:87], v[230:233], v[206:209], v[84:87]
	v_mfma_f32_16x16x32_bf16 v[80:83], v[238:241], v[206:209], v[80:83]
	v_mfma_f32_16x16x32_bf16 v[76:79], v[230:233], v[214:217], v[76:79]
	v_mfma_f32_16x16x32_bf16 v[72:75], v[238:241], v[214:217], v[72:75]
	v_mfma_f32_16x16x32_bf16 v[68:71], v[230:233], v[222:225], v[68:71]
	v_mfma_f32_16x16x32_bf16 v[64:67], v[238:241], v[222:225], v[64:67]
	s_setprio 0
	s_barrier
	s_add_i32 s6, s6, s57
	v_lshl_add_u64 v[146:147], v[146:147], 0, s[36:37]
	s_mov_b32 m0, s6
	s_nop 0
	global_load_lds_dwordx4 v[146:147], off
	v_lshl_add_u64 v[146:147], v[148:149], 0, s[36:37]
	s_add_i32 m0, s6, 0x2000
	s_nop 0
	global_load_lds_dwordx4 v[146:147], off
	s_mov_b32 m0, s72
	v_lshl_add_u64 v[146:147], v[194:195], 0, s[36:37]
	ds_read_b128 v[174:177], v157 offset:49152
	ds_read_b128 v[178:181], v157 offset:50176
	ds_read_b128 v[182:185], v157 offset:51200
	ds_read_b128 v[206:209], v157 offset:52224
	ds_read_b128 v[210:213], v157 offset:53248
	ds_read_b128 v[214:217], v157 offset:54272
	ds_read_b128 v[218:221], v157 offset:55296
	ds_read_b128 v[222:225], v157 offset:56320
	global_load_lds_dwordx4 v[146:147], off
	v_lshl_add_u64 v[146:147], v[196:197], 0, s[36:37]
	s_mov_b32 m0, s73
	s_nop 0
	global_load_lds_dwordx4 v[146:147], off
	s_add_u32 s54, s54, 0x40080
	s_addc_u32 s55, s55, 0
	s_add_i32 s6, s19, s57
	v_lshl_add_u64 v[146:147], s[54:55], 0, v[140:141]
	s_mov_b32 m0, s6
	s_nop 0
	global_load_lds_dwordx4 v[146:147], off
	v_lshl_add_u64 v[146:147], s[54:55], 0, v[132:133]
	s_add_i32 m0, s6, 0x2000
	s_nop 0
	global_load_lds_dwordx4 v[146:147], off
	s_waitcnt vmcnt(8)
	s_waitcnt lgkmcnt(0)
	s_barrier
	s_setprio 1
	v_mfma_f32_16x16x32_bf16 v[60:63], v[158:161], v[174:177], v[60:63]
	v_mfma_f32_16x16x32_bf16 v[56:59], v[166:169], v[174:177], v[56:59]
	v_mfma_f32_16x16x32_bf16 v[52:55], v[158:161], v[182:185], v[52:55]
	v_mfma_f32_16x16x32_bf16 v[48:51], v[166:169], v[182:185], v[48:51]
	v_mfma_f32_16x16x32_bf16 v[44:47], v[158:161], v[210:213], v[44:47]
	v_mfma_f32_16x16x32_bf16 v[40:43], v[166:169], v[210:213], v[40:43]
	v_mfma_f32_16x16x32_bf16 v[36:39], v[158:161], v[218:221], v[36:39]
	v_mfma_f32_16x16x32_bf16 v[32:35], v[166:169], v[218:221], v[32:35]
	v_mfma_f32_16x16x32_bf16 v[60:63], v[162:165], v[178:181], v[60:63]
	v_mfma_f32_16x16x32_bf16 v[56:59], v[170:173], v[178:181], v[56:59]
	v_mfma_f32_16x16x32_bf16 v[52:55], v[162:165], v[206:209], v[52:55]
	v_mfma_f32_16x16x32_bf16 v[48:51], v[170:173], v[206:209], v[48:51]
	v_mfma_f32_16x16x32_bf16 v[44:47], v[162:165], v[214:217], v[44:47]
	v_mfma_f32_16x16x32_bf16 v[40:43], v[170:173], v[214:217], v[40:43]
	v_mfma_f32_16x16x32_bf16 v[36:39], v[162:165], v[222:225], v[36:39]
	v_mfma_f32_16x16x32_bf16 v[32:35], v[170:173], v[222:225], v[32:35]
	v_mfma_f32_16x16x32_bf16 v[28:31], v[226:229], v[174:177], v[28:31]
	v_mfma_f32_16x16x32_bf16 v[24:27], v[234:237], v[174:177], v[24:27]
	v_mfma_f32_16x16x32_bf16 v[20:23], v[226:229], v[182:185], v[20:23]
	v_mfma_f32_16x16x32_bf16 v[16:19], v[234:237], v[182:185], v[16:19]
	v_mfma_f32_16x16x32_bf16 v[12:15], v[226:229], v[210:213], v[12:15]
	v_mfma_f32_16x16x32_bf16 v[8:11], v[234:237], v[210:213], v[8:11]
	v_mfma_f32_16x16x32_bf16 v[4:7], v[226:229], v[218:221], v[4:7]
	v_mfma_f32_16x16x32_bf16 v[0:3], v[234:237], v[218:221], v[0:3]
	v_mfma_f32_16x16x32_bf16 v[28:31], v[230:233], v[178:181], v[28:31]
	v_mfma_f32_16x16x32_bf16 v[24:27], v[238:241], v[178:181], v[24:27]
	v_mfma_f32_16x16x32_bf16 v[20:23], v[230:233], v[206:209], v[20:23]
	v_mfma_f32_16x16x32_bf16 v[16:19], v[238:241], v[206:209], v[16:19]
	v_mfma_f32_16x16x32_bf16 v[12:15], v[230:233], v[214:217], v[12:15]
	v_mfma_f32_16x16x32_bf16 v[8:11], v[238:241], v[214:217], v[8:11]
	v_mfma_f32_16x16x32_bf16 v[4:7], v[230:233], v[222:225], v[4:7]
	v_mfma_f32_16x16x32_bf16 v[0:3], v[238:241], v[222:225], v[0:3]
	s_setprio 0
	s_add_i32 s81, s81, 2
	s_add_u32 s52, s52, 0x100
	s_addc_u32 s53, s53, 0
	s_cmp_gt_u32 s81, 13
	s_barrier
	s_cbranch_scc0 .LBB0_386
	s_mov_b32 s100, 1
	v_lshl_add_u32 v158, s75, 10, v155
	ds_read2_b32 v[146:147], v158 offset1:16
	s_add_u32 s52, s10, 0xffffff00
	s_addc_u32 s53, s11, -1
	s_ashr_i32 s35, s34, 31
	s_lshl_b64 s[10:11], s[34:35], 8
	s_waitcnt lgkmcnt(0)
	v_mul_f32_e32 v184, 0xbfb8aa3b, v146
	v_mul_f32_e32 v206, v146, v146
	v_pk_mul_f32 v[168:169], v[124:125], v[184:185] op_sel_hi:[1,0]
	v_pk_mul_f32 v[170:171], v[126:127], v[184:185] op_sel_hi:[1,0]
	v_pk_mul_f32 v[172:173], v[120:121], v[184:185] op_sel_hi:[1,0]
	v_pk_mul_f32 v[174:175], v[122:123], v[184:185] op_sel_hi:[1,0]
	v_exp_f32_e32 v168, v168
	v_exp_f32_e32 v169, v169
	v_exp_f32_e32 v170, v170
	v_exp_f32_e32 v171, v171
	v_exp_f32_e32 v172, v172
	v_exp_f32_e32 v173, v173
	v_exp_f32_e32 v174, v174
	v_exp_f32_e32 v175, v175
	v_pk_mul_f32 v[176:177], v[124:125], v[92:93]
	v_pk_mul_f32 v[178:179], v[126:127], v[94:95]
	v_pk_mul_f32 v[180:181], v[120:121], v[88:89]
	v_pk_mul_f32 v[182:183], v[122:123], v[90:91]
	v_pk_add_f32 v[168:169], v[168:169], 1.0 op_sel_hi:[1,0]
	v_pk_add_f32 v[170:171], v[170:171], 1.0 op_sel_hi:[1,0]
	v_pk_add_f32 v[172:173], v[172:173], 1.0 op_sel_hi:[1,0]
	v_pk_add_f32 v[174:175], v[174:175], 1.0 op_sel_hi:[1,0]
	v_rcp_f32_e32 v168, v168
	v_rcp_f32_e32 v169, v169
	v_rcp_f32_e32 v170, v170
	v_rcp_f32_e32 v171, v171
	v_rcp_f32_e32 v172, v172
	v_rcp_f32_e32 v173, v173
	v_rcp_f32_e32 v174, v174
	v_rcp_f32_e32 v175, v175
	v_pk_mul_f32 v[176:177], v[176:177], v[206:207] op_sel_hi:[1,0]
	v_pk_mul_f32 v[178:179], v[178:179], v[206:207] op_sel_hi:[1,0]
	v_pk_mul_f32 v[180:181], v[180:181], v[206:207] op_sel_hi:[1,0]
	v_pk_mul_f32 v[182:183], v[182:183], v[206:207] op_sel_hi:[1,0]
	v_pk_mul_f32 v[176:177], v[176:177], v[168:169]
	v_pk_mul_f32 v[178:179], v[178:179], v[170:171]
	v_pk_mul_f32 v[180:181], v[180:181], v[172:173]
	v_pk_mul_f32 v[182:183], v[182:183], v[174:175]
	v_cvt_pk_bf16_f32 v160, v176, v177
	v_cvt_pk_bf16_f32 v161, v178, v179
	v_cvt_pk_bf16_f32 v162, v180, v181
	v_cvt_pk_bf16_f32 v163, v182, v183
	v_lshl_add_u64 v[152:153], v[134:135], 0, s[10:11]
	s_movk_i32 s6, 0x1600
	v_lshl_or_b32 v150, s74, 7, v156
	v_ashrrev_i32_e32 v151, 31, v150
	s_nop 1
	v_mov_b64_e32 v[148:149], s[30:31]
	v_mad_u64_u32 v[148:149], s[10:11], v152, s6, v[148:149]
	v_mov_b32_e32 v146, v149
	v_mad_u64_u32 v[152:153], s[10:11], v153, s6, v[146:147]
	v_mov_b32_e32 v149, v152
	v_mov_b32_e32 v146, v147
	v_lshl_add_u64 v[150:151], v[150:151], 1, v[148:149]
	global_store_dwordx4 v[150:151], v[160:163], off
	v_mul_f32_e32 v184, 0xbfb8aa3b, v146
	v_mul_f32_e32 v206, v146, v146
	v_pk_mul_f32 v[168:169], v[116:117], v[184:185] op_sel_hi:[1,0]
	v_pk_mul_f32 v[170:171], v[118:119], v[184:185] op_sel_hi:[1,0]
	v_pk_mul_f32 v[172:173], v[112:113], v[184:185] op_sel_hi:[1,0]
	v_pk_mul_f32 v[174:175], v[114:115], v[184:185] op_sel_hi:[1,0]
	v_exp_f32_e32 v168, v168
	v_exp_f32_e32 v169, v169
	v_exp_f32_e32 v170, v170
	v_exp_f32_e32 v171, v171
	v_exp_f32_e32 v172, v172
	v_exp_f32_e32 v173, v173
	v_exp_f32_e32 v174, v174
	v_exp_f32_e32 v175, v175
	v_pk_mul_f32 v[176:177], v[116:117], v[84:85]
	v_pk_mul_f32 v[178:179], v[118:119], v[86:87]
	v_pk_mul_f32 v[180:181], v[112:113], v[80:81]
	v_pk_mul_f32 v[182:183], v[114:115], v[82:83]
	v_pk_add_f32 v[168:169], v[168:169], 1.0 op_sel_hi:[1,0]
	v_pk_add_f32 v[170:171], v[170:171], 1.0 op_sel_hi:[1,0]
	v_pk_add_f32 v[172:173], v[172:173], 1.0 op_sel_hi:[1,0]
	v_pk_add_f32 v[174:175], v[174:175], 1.0 op_sel_hi:[1,0]
	v_rcp_f32_e32 v168, v168
	v_rcp_f32_e32 v169, v169
	v_rcp_f32_e32 v170, v170
	v_rcp_f32_e32 v171, v171
	v_rcp_f32_e32 v172, v172
	v_rcp_f32_e32 v173, v173
	v_rcp_f32_e32 v174, v174
	v_rcp_f32_e32 v175, v175
	v_pk_mul_f32 v[176:177], v[176:177], v[206:207] op_sel_hi:[1,0]
	v_pk_mul_f32 v[178:179], v[178:179], v[206:207] op_sel_hi:[1,0]
	v_pk_mul_f32 v[180:181], v[180:181], v[206:207] op_sel_hi:[1,0]
	v_pk_mul_f32 v[182:183], v[182:183], v[206:207] op_sel_hi:[1,0]
	v_pk_mul_f32 v[176:177], v[176:177], v[168:169]
	v_pk_mul_f32 v[178:179], v[178:179], v[170:171]
	v_pk_mul_f32 v[180:181], v[180:181], v[172:173]
	v_pk_mul_f32 v[182:183], v[182:183], v[174:175]
	v_cvt_pk_bf16_f32 v160, v176, v177
	v_cvt_pk_bf16_f32 v161, v178, v179
	v_cvt_pk_bf16_f32 v162, v180, v181
	v_cvt_pk_bf16_f32 v163, v182, v183
	s_mov_b32 s6, 0x16000
	s_nop 1
	v_add_co_u32_e32 v146, vcc, s6, v150
	s_nop 0
	v_addc_co_u32_e32 v147, vcc, 0, v151, vcc
	global_store_dwordx4 v[146:147], v[160:163], off
	ds_read2_b32 v[146:147], v158 offset0:32 offset1:48
	s_mov_b32 s6, 0x2c000
	s_waitcnt lgkmcnt(0)
	v_mul_f32_e32 v184, 0xbfb8aa3b, v146
	v_mul_f32_e32 v206, v146, v146
	v_pk_mul_f32 v[168:169], v[108:109], v[184:185] op_sel_hi:[1,0]
	v_pk_mul_f32 v[170:171], v[110:111], v[184:185] op_sel_hi:[1,0]
	v_pk_mul_f32 v[172:173], v[104:105], v[184:185] op_sel_hi:[1,0]
	v_pk_mul_f32 v[174:175], v[106:107], v[184:185] op_sel_hi:[1,0]
	v_exp_f32_e32 v168, v168
	v_exp_f32_e32 v169, v169
	v_exp_f32_e32 v170, v170
	v_exp_f32_e32 v171, v171
	v_exp_f32_e32 v172, v172
	v_exp_f32_e32 v173, v173
	v_exp_f32_e32 v174, v174
	v_exp_f32_e32 v175, v175
	v_pk_mul_f32 v[176:177], v[108:109], v[76:77]
	v_pk_mul_f32 v[178:179], v[110:111], v[78:79]
	v_pk_mul_f32 v[180:181], v[104:105], v[72:73]
	v_pk_mul_f32 v[182:183], v[106:107], v[74:75]
	v_pk_add_f32 v[168:169], v[168:169], 1.0 op_sel_hi:[1,0]
	v_pk_add_f32 v[170:171], v[170:171], 1.0 op_sel_hi:[1,0]
	v_pk_add_f32 v[172:173], v[172:173], 1.0 op_sel_hi:[1,0]
	v_pk_add_f32 v[174:175], v[174:175], 1.0 op_sel_hi:[1,0]
	v_rcp_f32_e32 v168, v168
	v_rcp_f32_e32 v169, v169
	v_rcp_f32_e32 v170, v170
	v_rcp_f32_e32 v171, v171
	v_rcp_f32_e32 v172, v172
	v_rcp_f32_e32 v173, v173
	v_rcp_f32_e32 v174, v174
	v_rcp_f32_e32 v175, v175
	v_pk_mul_f32 v[176:177], v[176:177], v[206:207] op_sel_hi:[1,0]
	v_pk_mul_f32 v[178:179], v[178:179], v[206:207] op_sel_hi:[1,0]
	v_pk_mul_f32 v[180:181], v[180:181], v[206:207] op_sel_hi:[1,0]
	v_pk_mul_f32 v[182:183], v[182:183], v[206:207] op_sel_hi:[1,0]
	v_pk_mul_f32 v[176:177], v[176:177], v[168:169]
	v_pk_mul_f32 v[178:179], v[178:179], v[170:171]
	v_pk_mul_f32 v[180:181], v[180:181], v[172:173]
	v_pk_mul_f32 v[182:183], v[182:183], v[174:175]
	v_cvt_pk_bf16_f32 v160, v176, v177
	v_cvt_pk_bf16_f32 v161, v178, v179
	v_cvt_pk_bf16_f32 v162, v180, v181
	v_cvt_pk_bf16_f32 v163, v182, v183
	s_nop 1
	v_mov_b32_e32 v146, v147
	v_add_co_u32_e32 v148, vcc, s6, v150
	v_addc_co_u32_e32 v149, vcc, 0, v151, vcc
	global_store_dwordx4 v[148:149], v[160:163], off
	v_mul_f32_e32 v184, 0xbfb8aa3b, v146
	v_mul_f32_e32 v206, v146, v146
	v_pk_mul_f32 v[168:169], v[100:101], v[184:185] op_sel_hi:[1,0]
	v_pk_mul_f32 v[170:171], v[102:103], v[184:185] op_sel_hi:[1,0]
	v_pk_mul_f32 v[172:173], v[96:97], v[184:185] op_sel_hi:[1,0]
	v_pk_mul_f32 v[174:175], v[98:99], v[184:185] op_sel_hi:[1,0]
	v_exp_f32_e32 v168, v168
	v_exp_f32_e32 v169, v169
	v_exp_f32_e32 v170, v170
	v_exp_f32_e32 v171, v171
	v_exp_f32_e32 v172, v172
	v_exp_f32_e32 v173, v173
	v_exp_f32_e32 v174, v174
	v_exp_f32_e32 v175, v175
	v_pk_mul_f32 v[176:177], v[100:101], v[68:69]
	v_pk_mul_f32 v[178:179], v[102:103], v[70:71]
	v_pk_mul_f32 v[180:181], v[96:97], v[64:65]
	v_pk_mul_f32 v[182:183], v[98:99], v[66:67]
	v_pk_add_f32 v[168:169], v[168:169], 1.0 op_sel_hi:[1,0]
	v_pk_add_f32 v[170:171], v[170:171], 1.0 op_sel_hi:[1,0]
	v_pk_add_f32 v[172:173], v[172:173], 1.0 op_sel_hi:[1,0]
	v_pk_add_f32 v[174:175], v[174:175], 1.0 op_sel_hi:[1,0]
	v_rcp_f32_e32 v168, v168
	v_rcp_f32_e32 v169, v169
	v_rcp_f32_e32 v170, v170
	v_rcp_f32_e32 v171, v171
	v_rcp_f32_e32 v172, v172
	v_rcp_f32_e32 v173, v173
	v_rcp_f32_e32 v174, v174
	v_rcp_f32_e32 v175, v175
	v_pk_mul_f32 v[176:177], v[176:177], v[206:207] op_sel_hi:[1,0]
	v_pk_mul_f32 v[178:179], v[178:179], v[206:207] op_sel_hi:[1,0]
	v_pk_mul_f32 v[180:181], v[180:181], v[206:207] op_sel_hi:[1,0]
	v_pk_mul_f32 v[182:183], v[182:183], v[206:207] op_sel_hi:[1,0]
	v_pk_mul_f32 v[176:177], v[176:177], v[168:169]
	v_pk_mul_f32 v[178:179], v[178:179], v[170:171]
	v_pk_mul_f32 v[180:181], v[180:181], v[172:173]
	v_pk_mul_f32 v[182:183], v[182:183], v[174:175]
	v_cvt_pk_bf16_f32 v160, v176, v177
	v_cvt_pk_bf16_f32 v161, v178, v179
	v_cvt_pk_bf16_f32 v162, v180, v181
	v_cvt_pk_bf16_f32 v163, v182, v183
	s_mov_b32 s6, 0x42000
	s_nop 1
	v_add_co_u32_e32 v146, vcc, s6, v150
	s_nop 0
	v_addc_co_u32_e32 v147, vcc, 0, v151, vcc
	global_store_dwordx4 v[146:147], v[160:163], off
	ds_read2_b32 v[146:147], v158 offset0:128 offset1:144
	s_mov_b32 s6, 0xb0000
	s_waitcnt lgkmcnt(0)
	v_mul_f32_e32 v184, 0xbfb8aa3b, v146
	v_mul_f32_e32 v206, v146, v146
	v_pk_mul_f32 v[168:169], v[60:61], v[184:185] op_sel_hi:[1,0]
	v_pk_mul_f32 v[170:171], v[62:63], v[184:185] op_sel_hi:[1,0]
	v_pk_mul_f32 v[172:173], v[56:57], v[184:185] op_sel_hi:[1,0]
	v_pk_mul_f32 v[174:175], v[58:59], v[184:185] op_sel_hi:[1,0]
	v_exp_f32_e32 v168, v168
	v_exp_f32_e32 v169, v169
	v_exp_f32_e32 v170, v170
	v_exp_f32_e32 v171, v171
	v_exp_f32_e32 v172, v172
	v_exp_f32_e32 v173, v173
	v_exp_f32_e32 v174, v174
	v_exp_f32_e32 v175, v175
	v_pk_mul_f32 v[176:177], v[60:61], v[28:29]
	v_pk_mul_f32 v[178:179], v[62:63], v[30:31]
	v_pk_mul_f32 v[180:181], v[56:57], v[24:25]
	v_pk_mul_f32 v[182:183], v[58:59], v[26:27]
	v_pk_add_f32 v[168:169], v[168:169], 1.0 op_sel_hi:[1,0]
	v_pk_add_f32 v[170:171], v[170:171], 1.0 op_sel_hi:[1,0]
	v_pk_add_f32 v[172:173], v[172:173], 1.0 op_sel_hi:[1,0]
	v_pk_add_f32 v[174:175], v[174:175], 1.0 op_sel_hi:[1,0]
	v_rcp_f32_e32 v168, v168
	v_rcp_f32_e32 v169, v169
	v_rcp_f32_e32 v170, v170
	v_rcp_f32_e32 v171, v171
	v_rcp_f32_e32 v172, v172
	v_rcp_f32_e32 v173, v173
	v_rcp_f32_e32 v174, v174
	v_rcp_f32_e32 v175, v175
	v_pk_mul_f32 v[176:177], v[176:177], v[206:207] op_sel_hi:[1,0]
	v_pk_mul_f32 v[178:179], v[178:179], v[206:207] op_sel_hi:[1,0]
	v_pk_mul_f32 v[180:181], v[180:181], v[206:207] op_sel_hi:[1,0]
	v_pk_mul_f32 v[182:183], v[182:183], v[206:207] op_sel_hi:[1,0]
	v_pk_mul_f32 v[176:177], v[176:177], v[168:169]
	v_pk_mul_f32 v[178:179], v[178:179], v[170:171]
	v_pk_mul_f32 v[180:181], v[180:181], v[172:173]
	v_pk_mul_f32 v[182:183], v[182:183], v[174:175]
	v_cvt_pk_bf16_f32 v160, v176, v177
	v_cvt_pk_bf16_f32 v161, v178, v179
	v_cvt_pk_bf16_f32 v162, v180, v181
	v_cvt_pk_bf16_f32 v163, v182, v183
	s_nop 1
	v_mov_b32_e32 v146, v147
	v_add_co_u32_e32 v148, vcc, s6, v150
	v_addc_co_u32_e32 v149, vcc, 0, v151, vcc
	global_store_dwordx4 v[148:149], v[160:163], off
	v_mul_f32_e32 v184, 0xbfb8aa3b, v146
	v_mul_f32_e32 v206, v146, v146
	v_pk_mul_f32 v[168:169], v[52:53], v[184:185] op_sel_hi:[1,0]
	v_pk_mul_f32 v[170:171], v[54:55], v[184:185] op_sel_hi:[1,0]
	v_pk_mul_f32 v[172:173], v[48:49], v[184:185] op_sel_hi:[1,0]
	v_pk_mul_f32 v[174:175], v[50:51], v[184:185] op_sel_hi:[1,0]
	v_exp_f32_e32 v168, v168
	v_exp_f32_e32 v169, v169
	v_exp_f32_e32 v170, v170
	v_exp_f32_e32 v171, v171
	v_exp_f32_e32 v172, v172
	v_exp_f32_e32 v173, v173
	v_exp_f32_e32 v174, v174
	v_exp_f32_e32 v175, v175
	v_pk_mul_f32 v[176:177], v[52:53], v[20:21]
	v_pk_mul_f32 v[178:179], v[54:55], v[22:23]
	v_pk_mul_f32 v[180:181], v[48:49], v[16:17]
	v_pk_mul_f32 v[182:183], v[50:51], v[18:19]
	v_pk_add_f32 v[168:169], v[168:169], 1.0 op_sel_hi:[1,0]
	v_pk_add_f32 v[170:171], v[170:171], 1.0 op_sel_hi:[1,0]
	v_pk_add_f32 v[172:173], v[172:173], 1.0 op_sel_hi:[1,0]
	v_pk_add_f32 v[174:175], v[174:175], 1.0 op_sel_hi:[1,0]
	v_rcp_f32_e32 v168, v168
	v_rcp_f32_e32 v169, v169
	v_rcp_f32_e32 v170, v170
	v_rcp_f32_e32 v171, v171
	v_rcp_f32_e32 v172, v172
	v_rcp_f32_e32 v173, v173
	v_rcp_f32_e32 v174, v174
	v_rcp_f32_e32 v175, v175
	v_pk_mul_f32 v[176:177], v[176:177], v[206:207] op_sel_hi:[1,0]
	v_pk_mul_f32 v[178:179], v[178:179], v[206:207] op_sel_hi:[1,0]
	v_pk_mul_f32 v[180:181], v[180:181], v[206:207] op_sel_hi:[1,0]
	v_pk_mul_f32 v[182:183], v[182:183], v[206:207] op_sel_hi:[1,0]
	v_pk_mul_f32 v[176:177], v[176:177], v[168:169]
	v_pk_mul_f32 v[178:179], v[178:179], v[170:171]
	v_pk_mul_f32 v[180:181], v[180:181], v[172:173]
	v_pk_mul_f32 v[182:183], v[182:183], v[174:175]
	v_cvt_pk_bf16_f32 v160, v176, v177
	v_cvt_pk_bf16_f32 v161, v178, v179
	v_cvt_pk_bf16_f32 v162, v180, v181
	v_cvt_pk_bf16_f32 v163, v182, v183
	s_mov_b32 s6, 0xc6000
	s_nop 1
	v_add_co_u32_e32 v146, vcc, s6, v150
	s_nop 0
	v_addc_co_u32_e32 v147, vcc, 0, v151, vcc
	global_store_dwordx4 v[146:147], v[160:163], off
	ds_read2_b32 v[146:147], v158 offset0:160 offset1:176
	s_mov_b32 s6, 0xdc000
	s_waitcnt lgkmcnt(0)
	v_mul_f32_e32 v184, 0xbfb8aa3b, v146
	v_mul_f32_e32 v206, v146, v146
	v_pk_mul_f32 v[168:169], v[44:45], v[184:185] op_sel_hi:[1,0]
	v_pk_mul_f32 v[170:171], v[46:47], v[184:185] op_sel_hi:[1,0]
	v_pk_mul_f32 v[172:173], v[40:41], v[184:185] op_sel_hi:[1,0]
	v_pk_mul_f32 v[174:175], v[42:43], v[184:185] op_sel_hi:[1,0]
	v_exp_f32_e32 v168, v168
	v_exp_f32_e32 v169, v169
	v_exp_f32_e32 v170, v170
	v_exp_f32_e32 v171, v171
	v_exp_f32_e32 v172, v172
	v_exp_f32_e32 v173, v173
	v_exp_f32_e32 v174, v174
	v_exp_f32_e32 v175, v175
	v_pk_mul_f32 v[176:177], v[44:45], v[12:13]
	v_pk_mul_f32 v[178:179], v[46:47], v[14:15]
	v_pk_mul_f32 v[180:181], v[40:41], v[8:9]
	v_pk_mul_f32 v[182:183], v[42:43], v[10:11]
	v_pk_add_f32 v[168:169], v[168:169], 1.0 op_sel_hi:[1,0]
	v_pk_add_f32 v[170:171], v[170:171], 1.0 op_sel_hi:[1,0]
	v_pk_add_f32 v[172:173], v[172:173], 1.0 op_sel_hi:[1,0]
	v_pk_add_f32 v[174:175], v[174:175], 1.0 op_sel_hi:[1,0]
	v_rcp_f32_e32 v168, v168
	v_rcp_f32_e32 v169, v169
	v_rcp_f32_e32 v170, v170
	v_rcp_f32_e32 v171, v171
	v_rcp_f32_e32 v172, v172
	v_rcp_f32_e32 v173, v173
	v_rcp_f32_e32 v174, v174
	v_rcp_f32_e32 v175, v175
	v_pk_mul_f32 v[176:177], v[176:177], v[206:207] op_sel_hi:[1,0]
	v_pk_mul_f32 v[178:179], v[178:179], v[206:207] op_sel_hi:[1,0]
	v_pk_mul_f32 v[180:181], v[180:181], v[206:207] op_sel_hi:[1,0]
	v_pk_mul_f32 v[182:183], v[182:183], v[206:207] op_sel_hi:[1,0]
	v_pk_mul_f32 v[176:177], v[176:177], v[168:169]
	v_pk_mul_f32 v[178:179], v[178:179], v[170:171]
	v_pk_mul_f32 v[180:181], v[180:181], v[172:173]
	v_pk_mul_f32 v[182:183], v[182:183], v[174:175]
	v_cvt_pk_bf16_f32 v158, v176, v177
	v_cvt_pk_bf16_f32 v159, v178, v179
	v_cvt_pk_bf16_f32 v160, v180, v181
	v_cvt_pk_bf16_f32 v161, v182, v183
	s_nop 1
	v_mov_b32_e32 v146, v147
	v_add_co_u32_e32 v148, vcc, s6, v150
	v_addc_co_u32_e32 v149, vcc, 0, v151, vcc
	global_store_dwordx4 v[148:149], v[158:161], off
	v_mul_f32_e32 v184, 0xbfb8aa3b, v146
	v_mul_f32_e32 v206, v146, v146
	v_pk_mul_f32 v[168:169], v[36:37], v[184:185] op_sel_hi:[1,0]
	v_pk_mul_f32 v[170:171], v[38:39], v[184:185] op_sel_hi:[1,0]
	v_pk_mul_f32 v[172:173], v[32:33], v[184:185] op_sel_hi:[1,0]
	v_pk_mul_f32 v[174:175], v[34:35], v[184:185] op_sel_hi:[1,0]
	v_exp_f32_e32 v168, v168
	v_exp_f32_e32 v169, v169
	v_exp_f32_e32 v170, v170
	v_exp_f32_e32 v171, v171
	v_exp_f32_e32 v172, v172
	v_exp_f32_e32 v173, v173
	v_exp_f32_e32 v174, v174
	v_exp_f32_e32 v175, v175
	v_pk_mul_f32 v[176:177], v[36:37], v[4:5]
	v_pk_mul_f32 v[178:179], v[38:39], v[6:7]
	v_pk_mul_f32 v[180:181], v[32:33], v[0:1]
	v_pk_mul_f32 v[182:183], v[34:35], v[2:3]
	v_pk_add_f32 v[168:169], v[168:169], 1.0 op_sel_hi:[1,0]
	v_pk_add_f32 v[170:171], v[170:171], 1.0 op_sel_hi:[1,0]
	v_pk_add_f32 v[172:173], v[172:173], 1.0 op_sel_hi:[1,0]
	v_pk_add_f32 v[174:175], v[174:175], 1.0 op_sel_hi:[1,0]
	v_rcp_f32_e32 v168, v168
	v_rcp_f32_e32 v169, v169
	v_rcp_f32_e32 v170, v170
	v_rcp_f32_e32 v171, v171
	v_rcp_f32_e32 v172, v172
	v_rcp_f32_e32 v173, v173
	v_rcp_f32_e32 v174, v174
	v_rcp_f32_e32 v175, v175
	v_pk_mul_f32 v[176:177], v[176:177], v[206:207] op_sel_hi:[1,0]
	v_pk_mul_f32 v[178:179], v[178:179], v[206:207] op_sel_hi:[1,0]
	v_pk_mul_f32 v[180:181], v[180:181], v[206:207] op_sel_hi:[1,0]
	v_pk_mul_f32 v[182:183], v[182:183], v[206:207] op_sel_hi:[1,0]
	v_pk_mul_f32 v[176:177], v[176:177], v[168:169]
	v_pk_mul_f32 v[178:179], v[178:179], v[170:171]
	v_pk_mul_f32 v[180:181], v[180:181], v[172:173]
	v_pk_mul_f32 v[182:183], v[182:183], v[174:175]
	v_cvt_pk_bf16_f32 v158, v176, v177
	v_cvt_pk_bf16_f32 v159, v178, v179
	v_cvt_pk_bf16_f32 v160, v180, v181
	v_cvt_pk_bf16_f32 v161, v182, v183
	s_nop 1
	v_add_co_u32_e32 v146, vcc, 0xf2000, v150
	s_nop 0
	v_addc_co_u32_e32 v147, vcc, 0, v151, vcc
	s_andn2_b64 vcc, exec, s[44:45]
	global_store_dwordx4 v[146:147], v[158:161], off
	s_cbranch_vccz .LBB0_382
	s_mov_b64 s[48:49], s[52:53]
	s_andn2_b64 vcc, exec, s[42:43]
	s_mov_b64 s[52:53], s[48:49]
	s_cbranch_vccnz .LBB0_383
